# PRE1 lam_bar^tau table spread over all 256 workgroups (index chunk c&15, taus c>>4 step 16) instead of 16 workgroups
# speedup vs baseline: 1.0051x; 1.0051x over previous
; #define FRESH_IDS() int tid_ = threadIdx.x; asm volatile("" : "+v"(tid_)); const int lane = tid_ & 63; const int gt = bx * (NWAVES * 64) + tid_; (void)lane; (void)gt
; #define INP(j) (((PH_EN >> (12 + (j))) & 1u) && IN(j))
; __global__ void __launch_bounds__(NWAVES * 64, 2) hybrid_fwd(Args args) {
;     ...
;     if (INP(0)) { FRESH_IDS();
;         for (int idx = gt; idx < DEPTH * NG * NP; idx += NGT) {
;             const int lg = idx >> 6, p = idx & 63;
;             const float lre = args.in[5][idx], lim = args.in[6][idx], dt = expf(args.in[7][lg]);
;             const float a = lre * dt, b = lim * dt;
;             for (int tau = 0; tau <= TCH; ++tau) { const float mg = expf(a * (float)tau); float sn, cs; sincosf(b * (float)tau, &sn, &cs); LP[(size_t)(lg * 33 + tau) * 64 + p] = (f32x2){mg * cs, mg * sn}; }
.LBB0_15:
	s_load_dwordx16 s[16:31], s[0:1], 0x0
	s_lshr_b32 s50, s51, 6
	s_lshl_b32 s2, s65, 3
	s_add_i32 s2, s2, s50
	s_lshl_b32 s43, s64, 3
	s_waitcnt lgkmcnt(0)
	v_writelane_b32 v249, s16, 9
	s_lshl_b32 s68, s64, 9
	s_nop 0
	v_writelane_b32 v249, s17, 10
	v_writelane_b32 v249, s18, 11
	v_writelane_b32 v249, s19, 12
	v_writelane_b32 v249, s20, 13
	v_writelane_b32 v249, s21, 14
	v_writelane_b32 v249, s22, 15
	v_writelane_b32 v249, s23, 16
	v_writelane_b32 v249, s24, 17
	v_writelane_b32 v249, s25, 18
	v_writelane_b32 v249, s26, 19
	v_writelane_b32 v249, s27, 20
	v_writelane_b32 v249, s28, 21
	v_writelane_b32 v249, s29, 22
	v_writelane_b32 v249, s30, 23
	v_writelane_b32 v249, s31, 24
	s_load_dwordx16 s[16:31], s[0:1], 0x40
	s_waitcnt lgkmcnt(0)
	v_writelane_b32 v249, s16, 25
	s_nop 1
	v_writelane_b32 v249, s17, 26
	v_writelane_b32 v249, s18, 27
	v_writelane_b32 v249, s19, 28
	v_writelane_b32 v249, s20, 29
	v_writelane_b32 v249, s21, 30
	v_writelane_b32 v249, s22, 31
	v_writelane_b32 v249, s23, 32
	v_writelane_b32 v249, s24, 33
	v_writelane_b32 v249, s25, 34
	v_writelane_b32 v249, s26, 35
	v_writelane_b32 v249, s27, 36
	v_writelane_b32 v249, s28, 37
	v_writelane_b32 v249, s29, 38
	v_writelane_b32 v249, s30, 39
	v_writelane_b32 v249, s31, 40
	v_writelane_b32 v249, s2, 41
	s_add_u32 s2, s58, 0xa240000
	s_addc_u32 s3, s59, 0
	s_add_u32 s33, s58, 0x46700000
	s_addc_u32 s54, s59, 0
	v_writelane_b32 v249, s2, 42
	s_cmp_lt_i32 s66, 1
	s_nop 0
	v_writelane_b32 v249, s3, 43
	s_cselect_b64 s[2:3], -1, 0
	s_cmp_gt_i32 s67, 0
	s_cselect_b64 s[4:5], -1, 0
	s_and_b64 s[2:3], s[2:3], s[4:5]
	s_andn2_b64 vcc, exec, s[2:3]
	s_cbranch_vccnz .LBB0_40
	v_readlane_b32 s4, v249, 0
	v_mov_b32_e32 v1, v0
	s_lshl_b32 s18, s4, 9
	s_movk_i32 s4, 0x2000
	s_and_b32 s100, s18, 0x1fff
	v_add_u32_e32 v2, s100, v1
	v_cmp_gt_i32_e32 vcc, s4, v2
	s_and_saveexec_b64 s[10:11], vcc
	s_mov_b32 s42, s68
	s_cbranch_execz .LBB0_33
	v_and_b32_e32 v1, 63, v1
	v_lshlrev_b32_e32 v4, 3, v1
	v_mov_b32_e32 v5, 0
	v_lshl_add_u64 v[6:7], s[58:59], 0, v[4:5]
	s_mov_b64 s[4:5], 0xa000000
	v_lshl_add_u64 v[6:7], v[6:7], 0, s[4:5]
	s_mov_b64 s[14:15], 0
	s_mov_b32 s19, 0x3fb8aa3b
	s_mov_b32 s20, 0xc2ce8ed0
	s_mov_b32 s21, 0x42b17218
	v_mov_b32_e32 v1, 0x7f800000
	s_brev_b32 s22, 18
	s_mov_b32 s23, 0xfe5163ab
	s_mov_b32 s24, 0x3c439041
	s_mov_b32 s25, 0xdb629599
	s_mov_b32 s26, 0xf534ddc0
	s_mov_b32 s27, 0xfc2757d1
	s_mov_b32 s28, 0x4e441529
	s_mov_b32 s29, 0xa2f9836e
	s_mov_b32 s30, 0x3fc90fda
	s_mov_b32 s31, 0x3f22f983
	s_mov_b32 s34, 0xbfc90fda
	v_mov_b32_e32 v12, 0x3c0881c4
	v_mov_b32_e32 v13, 0xbab64f3b
	s_brev_b32 s35, 1
	s_movk_i32 s36, 0x1f8
	v_mov_b32_e32 v14, 0x3ab69700
	s_mov_b32 s37, 0x43000000
	s_mov_b32 s38, 0x42b17217
	s_mov_b32 s39, 0xc1880000
	s_movk_i32 s40, 0x1fff
	v_not_b32_e32 v15, 63
	v_not_b32_e32 v16, 31
	v_mov_b32_e32 v17, 0x7fc00000
	v_mov_b32_e32 v18, 0x7f000000
	s_branch .LBB0_19

; __global__ void __launch_bounds__(NWAVES * 64, 2) hybrid_fwd(Args args) {
;     ...
;         for (int idx = gt; idx < DEPTH * NG * NP; idx += NGT) {
;             const int lg = idx >> 6, p = idx & 63;
;             const float lre = args.in[5][idx], lim = args.in[6][idx], dt = expf(args.in[7][lg]);
;             const float a = lre * dt, b = lim * dt;
;             for (int tau = 0; tau <= TCH; ++tau) { const float mg = expf(a * (float)tau); float sn, cs; sincosf(b * (float)tau, &sn, &cs); LP[(size_t)(lg * 33 + tau) * 64 + p] = (f32x2){mg * cs, mg * sn}; }
.LBB0_19:
	s_load_dwordx16 s[68:83], s[0:1], 0x0
	v_ashrrev_i32_e32 v10, 6, v2
	v_ashrrev_i32_e32 v11, 31, v10
	v_ashrrev_i32_e32 v3, 31, v2
	v_readlane_b32 s41, v249, 0
	s_waitcnt lgkmcnt(0)
	s_lshr_b32 s41, s41, 4
	v_lshl_add_u64 v[8:9], v[10:11], 2, s[82:83]
	global_load_dword v4, v[8:9], off
	v_lshlrev_b64 v[8:9], 2, v[2:3]
	v_lshl_add_u64 v[20:21], s[78:79], 0, v[8:9]
	v_lshl_add_u64 v[22:23], s[80:81], 0, v[8:9]
	global_load_dword v8, v[20:21], off
	global_load_dword v9, v[22:23], off
	v_lshl_add_u32 v10, v10, 5, v10
	s_waitcnt vmcnt(2)
	v_mul_f32_e32 v11, 0x3fb8aa3b, v4
	v_fma_f32 v19, v4, s19, -v11
	v_rndne_f32_e32 v20, v11
	v_fmac_f32_e32 v19, 0x32a5705f, v4
	v_sub_f32_e32 v11, v11, v20
	v_add_f32_e32 v11, v11, v19
	v_cvt_i32_f32_e32 v20, v20
	v_exp_f32_e32 v19, v11
	v_cmp_ngt_f32_e32 vcc, s20, v4
	v_ashrrev_i32_e32 v11, 31, v10
	v_lshlrev_b64 v[10:11], 9, v[10:11]
	v_ldexp_f32 v19, v19, v20
	v_cndmask_b32_e32 v19, 0, v19, vcc
	v_cmp_nlt_f32_e32 vcc, s21, v4
	v_lshl_add_u64 v[10:11], v[6:7], 0, v[10:11]
	s_nop 0
	v_cndmask_b32_e32 v4, v1, v19, vcc
	s_waitcnt vmcnt(1)
	v_mul_f32_e32 v19, v8, v4
	s_waitcnt vmcnt(0)
	v_mul_f32_e32 v20, v9, v4
	s_lshl_b32 s100, s41, 9
	s_mov_b32 s101, 0
	v_lshl_add_u64 v[10:11], v[10:11], 0, s[100:101]
	s_branch .LBB0_21
.LBB0_20:
	s_or_b64 exec, exec, s[4:5]
	v_mul_f32_e32 v23, v19, v23
	v_mul_f32_e32 v25, 0x3fb8aa3b, v23
	v_fma_f32 v26, v23, s19, -v25
	v_rndne_f32_e32 v27, v25
	v_fmac_f32_e32 v26, 0x32a5705f, v23
	v_sub_f32_e32 v25, v25, v27
	v_add_f32_e32 v25, v25, v26
	v_cvt_i32_f32_e32 v26, v27
	v_exp_f32_e32 v25, v25
	v_cmp_ngt_f32_e32 vcc, s20, v23
	v_xor_b32_e32 v22, v22, v21
	s_add_i32 s41, s41, 16
	v_ldexp_f32 v25, v25, v26
	v_cndmask_b32_e32 v25, 0, v25, vcc
	v_cmp_nlt_f32_e32 vcc, s21, v23
	s_mov_b64 s[4:5], 0x2000
	s_cmp_gt_u32 s41, 32
	v_cndmask_b32_e32 v23, v1, v25, vcc
	v_mul_f32_e32 v25, v4, v4
	v_fmamk_f32 v26, v25, 0xb94c1982, v12
	v_fmaak_f32 v26, v25, v26, 0xbe2aaa9d
	v_mul_f32_e32 v26, v25, v26
	v_fmac_f32_e32 v4, v4, v26
	v_fmamk_f32 v26, v25, 0x37d75334, v13
	v_fmaak_f32 v26, v25, v26, 0x3d2aabf7
	v_fmaak_f32 v26, v25, v26, 0xbf000004
	v_fma_f32 v25, v25, v26, 1.0
	v_lshlrev_b32_e32 v26, 30, v24
	v_and_b32_e32 v24, 1, v24
	v_cmp_eq_u32_e32 vcc, 0, v24
	v_and_b32_e32 v27, 0x80000000, v26
	s_nop 0
	v_cndmask_b32_e32 v24, v25, v4, vcc
	v_xor_b32_e32 v4, 0x80000000, v4
	v_xor_b32_e32 v22, v22, v24
	v_cndmask_b32_e32 v4, v4, v25, vcc
	v_xor_b32_e32 v22, v22, v27
	v_bitop3_b32 v4, v4, v26, s35 bitop3:0x78
	v_cmp_class_f32_e64 vcc, v21, s36
	s_nop 1
	v_cndmask_b32_e32 v4, v17, v4, vcc
	v_cndmask_b32_e32 v21, v17, v22, vcc
	v_mul_f32_e32 v22, v23, v4
	v_mul_f32_e32 v23, v23, v21
	global_store_dwordx2 v[10:11], v[22:23], off
	v_lshl_add_u64 v[10:11], v[10:11], 0, s[4:5]
	s_cbranch_scc1 .LBB0_25
